# MLA loop: softmax(t) VALU issued inside QK(t+1) MFMA chain, PV fragment reads issued early into freed chain buffers
# speedup vs baseline: 1.0724x; 1.0085x over previous
.LBB0_564:
	s_mul_hi_u32 s7, s4, 0xaaaaaaab
	s_lshr_b32 s7, s7, 1
	s_mul_i32 s7, s7, 0x9000
	v_subrev_u32_e32 v64, s7, v166
	v_add_u32_e32 v200, s36, v175
	v_add_u32_e32 v201, v200, v64
	v_subrev_u32_e32 v202, s7, v172
	v_subrev_u32_e32 v203, s7, v173
	v_subrev_u32_e32 v204, s7, v174
	v_add_u32_e32 v202, v200, v202
	v_add_u32_e32 v203, v200, v203
	v_add_u32_e32 v204, v200, v204
	ds_read_b128 v[64:67], v201 offset:12288
	ds_read_b128 v[232:235], v202 offset:12288
	ds_read_b128 v[236:239], v203 offset:12288
	ds_read_b128 v[240:243], v204 offset:12288
	ds_read_b128 v[244:247], v201 offset:12416
	ds_read_b128 v[248:251], v202 offset:12416
	ds_read_b128 v[252:255], v203 offset:12416
	s_add_i32 s7, s5, 0xffffa000
	s_and_b32 s7, s7, 0x6000
	s_add_i32 s7, s7, 16
	s_waitcnt lgkmcnt(6)
	v_mfma_f32_32x32x16_bf16 v[64:79], v[64:67], v[142:145], 0
	v_max_f32_e32 v177, v80, v80
	v_max_f32_e32 v176, v81, v81
	v_max_f32_e32 v176, v177, v176
	v_max3_f32 v176, v176, v82, v83
	v_max3_f32 v176, v176, v84, v85
	v_max3_f32 v176, v176, v86, v87
	s_waitcnt lgkmcnt(5)
	v_mfma_f32_32x32x16_bf16 v[64:79], v[232:235], v[138:141], v[64:79]
	ds_read_b128 v[232:235], v204 offset:12416
	v_max3_f32 v176, v176, v88, v89
	v_max3_f32 v176, v176, v90, v91
	v_max3_f32 v176, v176, v92, v93
	v_max3_f32 v176, v176, v94, v95
	v_mov_b32_e32 v177, v176
	s_waitcnt lgkmcnt(5)
	v_mfma_f32_32x32x16_bf16 v[64:79], v[236:239], v[134:137], v[64:79]
	ds_read_b128 v[236:239], v201 offset:12544
	v_permlane32_swap_b32_e32 v176, v177
	v_max_f32_e32 v177, v177, v177
	v_max_f32_e32 v176, v176, v176
	v_max_f32_e32 v176, v176, v177
	v_add_f32_e32 v177, 0x41000000, v165
	v_cmp_gt_f32_e32 vcc, v176, v177
	s_cbranch_vccz .LBB0_566
	v_max_f32_e32 v176, v176, v176
	v_max_f32_e32 v177, v165, v165
	v_max_f32_e32 v177, v177, v176
	v_sub_f32_e32 v165, v165, v177
	v_exp_f32_e32 v176, v165
	v_mov_b32_e32 v165, v177
	v_pk_mul_f32 v[62:63], v[62:63], v[176:177] op_sel_hi:[1,0]
	v_pk_mul_f32 v[60:61], v[60:61], v[176:177] op_sel_hi:[1,0]
	v_pk_mul_f32 v[58:59], v[58:59], v[176:177] op_sel_hi:[1,0]
	v_pk_mul_f32 v[56:57], v[56:57], v[176:177] op_sel_hi:[1,0]
	v_pk_mul_f32 v[54:55], v[54:55], v[176:177] op_sel_hi:[1,0]
	v_pk_mul_f32 v[52:53], v[52:53], v[176:177] op_sel_hi:[1,0]
	v_pk_mul_f32 v[50:51], v[50:51], v[176:177] op_sel_hi:[1,0]
	v_pk_mul_f32 v[48:49], v[48:49], v[176:177] op_sel_hi:[1,0]
	v_pk_mul_f32 v[46:47], v[46:47], v[176:177] op_sel_hi:[1,0]
	v_pk_mul_f32 v[44:45], v[44:45], v[176:177] op_sel_hi:[1,0]
	v_pk_mul_f32 v[42:43], v[42:43], v[176:177] op_sel_hi:[1,0]
	v_pk_mul_f32 v[40:41], v[40:41], v[176:177] op_sel_hi:[1,0]
	v_pk_mul_f32 v[38:39], v[38:39], v[176:177] op_sel_hi:[1,0]
	v_pk_mul_f32 v[36:37], v[36:37], v[176:177] op_sel_hi:[1,0]
	v_pk_mul_f32 v[34:35], v[34:35], v[176:177] op_sel_hi:[1,0]
	v_pk_mul_f32 v[32:33], v[32:33], v[176:177] op_sel_hi:[1,0]
	v_pk_mul_f32 v[30:31], v[30:31], v[176:177] op_sel_hi:[1,0]
	v_pk_mul_f32 v[28:29], v[28:29], v[176:177] op_sel_hi:[1,0]
	v_pk_mul_f32 v[26:27], v[26:27], v[176:177] op_sel_hi:[1,0]
	v_pk_mul_f32 v[24:25], v[24:25], v[176:177] op_sel_hi:[1,0]
	v_pk_mul_f32 v[22:23], v[22:23], v[176:177] op_sel_hi:[1,0]
	v_pk_mul_f32 v[20:21], v[20:21], v[176:177] op_sel_hi:[1,0]
	v_pk_mul_f32 v[18:19], v[18:19], v[176:177] op_sel_hi:[1,0]
	v_pk_mul_f32 v[16:17], v[16:17], v[176:177] op_sel_hi:[1,0]
	v_pk_mul_f32 v[14:15], v[14:15], v[176:177] op_sel_hi:[1,0]
	v_pk_mul_f32 v[12:13], v[12:13], v[176:177] op_sel_hi:[1,0]
	v_pk_mul_f32 v[10:11], v[10:11], v[176:177] op_sel_hi:[1,0]
	v_pk_mul_f32 v[8:9], v[8:9], v[176:177] op_sel_hi:[1,0]
	v_pk_mul_f32 v[6:7], v[6:7], v[176:177] op_sel_hi:[1,0]
	v_pk_mul_f32 v[4:5], v[4:5], v[176:177] op_sel_hi:[1,0]
	v_pk_mul_f32 v[2:3], v[2:3], v[176:177] op_sel_hi:[1,0]
	v_pk_mul_f32 v[0:1], v[0:1], v[176:177] op_sel_hi:[1,0]
	v_mul_f32_e32 v164, v164, v176
.LBB0_566:
	s_waitcnt lgkmcnt(5)
	v_mfma_f32_32x32x16_bf16 v[64:79], v[240:243], v[130:133], v[64:79]
	ds_read_b128 v[240:243], v202 offset:12544
	v_sub_f32_e32 v80, v80, v165
	v_exp_f32_e32 v80, v80
	v_sub_f32_e32 v81, v81, v165
	v_exp_f32_e32 v81, v81
	s_waitcnt lgkmcnt(5)
	v_mfma_f32_32x32x16_bf16 v[64:79], v[244:247], v[126:129], v[64:79]
	ds_read_b128 v[244:247], v203 offset:12544
	v_add_f32_e32 v205, 0, v80
	v_sub_f32_e32 v82, v82, v165
	v_exp_f32_e32 v82, v82
	v_add_f32_e32 v205, v81, v205
	v_cvt_pk_bf16_f32 v206, v80, v81
	s_waitcnt lgkmcnt(5)
	v_mfma_f32_32x32x16_bf16 v[64:79], v[248:251], v[122:125], v[64:79]
	ds_read_b128 v[248:251], v204 offset:12544
	v_add_u32_e32 v201, s7, v162
	v_add_u32_e32 v202, s7, v163
	v_add_u32_e32 v203, s7, v161
	v_add_u32_e32 v204, s7, v160
	v_sub_f32_e32 v83, v83, v165
	s_waitcnt lgkmcnt(5)
	v_mfma_f32_32x32x16_bf16 v[64:79], v[252:255], v[118:121], v[64:79]
	ds_read_b64 v[252:253], v201
	ds_read_b64 v[254:255], v202
	v_exp_f32_e32 v83, v83
	v_add_f32_e32 v205, v82, v205
	v_sub_f32_e32 v84, v84, v165
	v_exp_f32_e32 v84, v84
	s_waitcnt lgkmcnt(6)
	v_mfma_f32_32x32x16_bf16 v[64:79], v[232:235], v[114:117], v[64:79]
	ds_read_b64 v[232:233], v201 offset:2048
	ds_read_b64 v[234:235], v202 offset:2048
	v_add_f32_e32 v205, v83, v205
	v_cvt_pk_bf16_f32 v207, v82, v83
	v_sub_f32_e32 v85, v85, v165
	v_exp_f32_e32 v85, v85
	v_add_f32_e32 v205, v84, v205
	s_waitcnt lgkmcnt(7)
	v_mfma_f32_32x32x16_bf16 v[64:79], v[236:239], v[110:113], v[64:79]
	ds_read_b64 v[236:237], v201 offset:4096
	ds_read_b64 v[238:239], v202 offset:4096
	v_sub_f32_e32 v86, v86, v165
	v_exp_f32_e32 v86, v86
	v_add_f32_e32 v205, v85, v205
	v_cvt_pk_bf16_f32 v208, v84, v85
	v_sub_f32_e32 v87, v87, v165
	s_waitcnt lgkmcnt(8)
	v_mfma_f32_32x32x16_bf16 v[64:79], v[240:243], v[106:109], v[64:79]
	ds_read_b64 v[240:241], v201 offset:6144
	ds_read_b64 v[242:243], v202 offset:6144
	v_exp_f32_e32 v87, v87
	v_add_f32_e32 v205, v86, v205
	v_sub_f32_e32 v88, v88, v165
	v_exp_f32_e32 v88, v88
	s_waitcnt lgkmcnt(9)
	v_mfma_f32_32x32x16_bf16 v[64:79], v[244:247], v[102:105], v[64:79]
	ds_read_b64 v[244:245], v203
	ds_read_b64 v[246:247], v204
	v_add_f32_e32 v205, v87, v205
	v_cvt_pk_bf16_f32 v209, v86, v87
	v_sub_f32_e32 v89, v89, v165
	v_exp_f32_e32 v89, v89
	v_add_f32_e32 v205, v88, v205
	s_waitcnt lgkmcnt(10)
	v_mfma_f32_32x32x16_bf16 v[64:79], v[248:251], v[98:101], v[64:79]
	ds_read_b64 v[248:249], v203 offset:2048
	ds_read_b64 v[250:251], v204 offset:2048
	v_sub_f32_e32 v90, v90, v165
	v_exp_f32_e32 v90, v90
	v_add_f32_e32 v205, v89, v205
	v_cvt_pk_bf16_f32 v210, v88, v89
	v_sub_f32_e32 v91, v91, v165
	s_waitcnt lgkmcnt(10)
	v_mfma_f32_32x32x16_bf16 v[48:63], v[252:255], v[206:209], v[48:63]
	ds_read_b64 v[80:81], v203 offset:4096
	ds_read_b64 v[82:83], v204 offset:4096
	ds_read_b64 v[84:85], v203 offset:6144
	ds_read_b64 v[86:87], v204 offset:6144
	v_exp_f32_e32 v91, v91
	v_add_f32_e32 v205, v90, v205
	v_sub_f32_e32 v92, v92, v165
	v_exp_f32_e32 v92, v92
	s_waitcnt lgkmcnt(12)
	v_mfma_f32_32x32x16_bf16 v[32:47], v[232:235], v[206:209], v[32:47]
	v_add_f32_e32 v205, v91, v205
	v_cvt_pk_bf16_f32 v211, v90, v91
	v_sub_f32_e32 v93, v93, v165
	v_exp_f32_e32 v93, v93
	v_add_f32_e32 v205, v92, v205
	s_waitcnt lgkmcnt(10)
	v_mfma_f32_32x32x16_bf16 v[16:31], v[236:239], v[206:209], v[16:31]
	v_sub_f32_e32 v94, v94, v165
	v_exp_f32_e32 v94, v94
	v_add_f32_e32 v205, v93, v205
	v_cvt_pk_bf16_f32 v212, v92, v93
	v_sub_f32_e32 v95, v95, v165
	s_waitcnt lgkmcnt(8)
	v_mfma_f32_32x32x16_bf16 v[0:15], v[240:243], v[206:209], v[0:15]
	v_exp_f32_e32 v95, v95
	v_add_f32_e32 v205, v94, v205
	v_add_f32_e32 v205, v95, v205
	v_cvt_pk_bf16_f32 v213, v94, v95
	v_add_f32_e32 v164, v164, v205
	s_add_i32 s6, s6, 1
	s_addk_i32 s5, 0x2000
	s_addk_i32 s36, 0x3000
	s_add_i32 s4, s4, 1
	v_lshl_add_u64 v[150:151], v[150:151], 0, 64
	v_lshl_add_u64 v[152:153], v[152:153], 0, v[148:149]
	v_lshl_add_u64 v[154:155], v[154:155], 0, v[146:147]
	v_lshl_add_u64 v[156:157], v[156:157], 0, v[96:97]
	s_cmp_eq_u32 s36, 0x192000
	s_waitcnt lgkmcnt(6)
	v_mfma_f32_32x32x16_bf16 v[48:63], v[244:247], v[210:213], v[48:63]
	s_waitcnt lgkmcnt(4)
	v_mfma_f32_32x32x16_bf16 v[32:47], v[248:251], v[210:213], v[32:47]
	s_waitcnt lgkmcnt(2)
	v_mfma_f32_32x32x16_bf16 v[16:31], v[80:83], v[210:213], v[16:31]
	s_waitcnt lgkmcnt(0)
	v_mfma_f32_32x32x16_bf16 v[0:15], v[84:87], v[210:213], v[0:15]
	s_cbranch_scc1 .LBB0_766
	v_mov_b64_e32 v[94:95], v[78:79]
	v_mov_b64_e32 v[92:93], v[76:77]
	v_mov_b64_e32 v[90:91], v[74:75]
	v_mov_b64_e32 v[88:89], v[72:73]
	v_mov_b64_e32 v[86:87], v[70:71]
	v_mov_b64_e32 v[84:85], v[68:69]
	v_mov_b64_e32 v[82:83], v[66:67]
	v_mov_b64_e32 v[80:81], v[64:65]
	s_branch .LBB0_562

.LBB0_611:
	s_mul_hi_u32 s6, s0, 0xaaaaaaab
	s_lshr_b32 s6, s6, 1
	s_mul_i32 s6, s6, 0x9000
	v_subrev_u32_e32 v64, s6, v201
	v_add_u32_e32 v216, s4, v209
	v_add_u32_e32 v212, v216, v64
	v_subrev_u32_e32 v213, s6, v206
	v_subrev_u32_e32 v214, s6, v207
	v_subrev_u32_e32 v215, s6, v208
	v_add_u32_e32 v213, v216, v213
	v_add_u32_e32 v214, v216, v214
	v_add_u32_e32 v215, v216, v215
	ds_read_b128 v[64:67], v212 offset:12288
	ds_read_b128 v[232:235], v213 offset:12288
	ds_read_b128 v[236:239], v214 offset:12288
	ds_read_b128 v[240:243], v215 offset:12288
	ds_read_b128 v[244:247], v212 offset:12416
	ds_read_b128 v[248:251], v213 offset:12416
	ds_read_b128 v[252:255], v214 offset:12416
	s_and_b32 s6, s36, 0x6000
	s_add_i32 s6, s6, 16
	s_waitcnt lgkmcnt(6)
	v_mfma_f32_32x32x16_bf16 v[64:79], v[64:67], v[142:145], 0
	v_max_f32_e32 v211, v80, v80
	v_max_f32_e32 v210, v81, v81
	v_max_f32_e32 v210, v211, v210
	v_max3_f32 v210, v210, v82, v83
	v_max3_f32 v210, v210, v84, v85
	v_max3_f32 v210, v210, v86, v87
	s_waitcnt lgkmcnt(5)
	v_mfma_f32_32x32x16_bf16 v[64:79], v[232:235], v[138:141], v[64:79]
	ds_read_b128 v[232:235], v215 offset:12416
	v_max3_f32 v210, v210, v88, v89
	v_max3_f32 v210, v210, v90, v91
	v_max3_f32 v210, v210, v92, v93
	v_max3_f32 v210, v210, v94, v95
	v_mov_b32_e32 v211, v210
	s_waitcnt lgkmcnt(5)
	v_mfma_f32_32x32x16_bf16 v[64:79], v[236:239], v[134:137], v[64:79]
	ds_read_b128 v[236:239], v212 offset:12544
	v_permlane32_swap_b32_e32 v210, v211
	v_max_f32_e32 v211, v211, v211
	v_max_f32_e32 v210, v210, v210
	v_max_f32_e32 v210, v210, v211
	v_add_f32_e32 v211, 0x41000000, v198
	v_cmp_gt_f32_e32 vcc, v210, v211
	s_cbranch_vccz .LBB0_613
	v_max_f32_e32 v210, v210, v210
	v_max_f32_e32 v211, v198, v198
	v_max_f32_e32 v210, v211, v210
	v_sub_f32_e32 v198, v198, v210
	v_exp_f32_e32 v198, v198
	s_nop 0
	v_pk_mul_f32 v[62:63], v[62:63], v[198:199] op_sel_hi:[1,0]
	v_pk_mul_f32 v[60:61], v[60:61], v[198:199] op_sel_hi:[1,0]
	v_pk_mul_f32 v[58:59], v[58:59], v[198:199] op_sel_hi:[1,0]
	v_pk_mul_f32 v[56:57], v[56:57], v[198:199] op_sel_hi:[1,0]
	v_pk_mul_f32 v[54:55], v[54:55], v[198:199] op_sel_hi:[1,0]
	v_pk_mul_f32 v[52:53], v[52:53], v[198:199] op_sel_hi:[1,0]
	v_pk_mul_f32 v[50:51], v[50:51], v[198:199] op_sel_hi:[1,0]
	v_pk_mul_f32 v[48:49], v[48:49], v[198:199] op_sel_hi:[1,0]
	v_pk_mul_f32 v[46:47], v[46:47], v[198:199] op_sel_hi:[1,0]
	v_pk_mul_f32 v[44:45], v[44:45], v[198:199] op_sel_hi:[1,0]
	v_pk_mul_f32 v[42:43], v[42:43], v[198:199] op_sel_hi:[1,0]
	v_pk_mul_f32 v[40:41], v[40:41], v[198:199] op_sel_hi:[1,0]
	v_pk_mul_f32 v[38:39], v[38:39], v[198:199] op_sel_hi:[1,0]
	v_pk_mul_f32 v[36:37], v[36:37], v[198:199] op_sel_hi:[1,0]
	v_pk_mul_f32 v[34:35], v[34:35], v[198:199] op_sel_hi:[1,0]
	v_pk_mul_f32 v[32:33], v[32:33], v[198:199] op_sel_hi:[1,0]
	v_pk_mul_f32 v[30:31], v[30:31], v[198:199] op_sel_hi:[1,0]
	v_pk_mul_f32 v[28:29], v[28:29], v[198:199] op_sel_hi:[1,0]
	v_pk_mul_f32 v[26:27], v[26:27], v[198:199] op_sel_hi:[1,0]
	v_pk_mul_f32 v[24:25], v[24:25], v[198:199] op_sel_hi:[1,0]
	v_pk_mul_f32 v[22:23], v[22:23], v[198:199] op_sel_hi:[1,0]
	v_pk_mul_f32 v[20:21], v[20:21], v[198:199] op_sel_hi:[1,0]
	v_pk_mul_f32 v[18:19], v[18:19], v[198:199] op_sel_hi:[1,0]
	v_pk_mul_f32 v[16:17], v[16:17], v[198:199] op_sel_hi:[1,0]
	v_pk_mul_f32 v[14:15], v[14:15], v[198:199] op_sel_hi:[1,0]
	v_pk_mul_f32 v[12:13], v[12:13], v[198:199] op_sel_hi:[1,0]
	v_pk_mul_f32 v[10:11], v[10:11], v[198:199] op_sel_hi:[1,0]
	v_pk_mul_f32 v[8:9], v[8:9], v[198:199] op_sel_hi:[1,0]
	v_pk_mul_f32 v[6:7], v[6:7], v[198:199] op_sel_hi:[1,0]
	v_pk_mul_f32 v[4:5], v[4:5], v[198:199] op_sel_hi:[1,0]
	v_pk_mul_f32 v[2:3], v[2:3], v[198:199] op_sel_hi:[1,0]
	v_pk_mul_f32 v[0:1], v[0:1], v[198:199] op_sel_hi:[1,0]
	v_mul_f32_e32 v177, v177, v198
	v_mov_b32_e32 v198, v210
.LBB0_613:
	s_waitcnt lgkmcnt(5)
	v_mfma_f32_32x32x16_bf16 v[64:79], v[240:243], v[130:133], v[64:79]
	ds_read_b128 v[240:243], v213 offset:12544
	v_sub_f32_e32 v80, v80, v198
	v_exp_f32_e32 v80, v80
	v_sub_f32_e32 v81, v81, v198
	v_exp_f32_e32 v81, v81
	s_waitcnt lgkmcnt(5)
	v_mfma_f32_32x32x16_bf16 v[64:79], v[244:247], v[126:129], v[64:79]
	ds_read_b128 v[244:247], v214 offset:12544
	v_add_f32_e32 v217, 0, v80
	v_sub_f32_e32 v82, v82, v198
	v_exp_f32_e32 v82, v82
	v_add_f32_e32 v217, v81, v217
	v_cvt_pk_bf16_f32 v218, v80, v81
	s_waitcnt lgkmcnt(5)
	v_mfma_f32_32x32x16_bf16 v[64:79], v[248:251], v[122:125], v[64:79]
	ds_read_b128 v[248:251], v215 offset:12544
	v_add_u32_e32 v212, s6, v157
	v_add_u32_e32 v213, s6, v176
	v_add_u32_e32 v214, s6, v153
	v_add_u32_e32 v215, s6, v149
	v_sub_f32_e32 v83, v83, v198
	s_waitcnt lgkmcnt(5)
	v_mfma_f32_32x32x16_bf16 v[64:79], v[252:255], v[118:121], v[64:79]
	ds_read_b64 v[252:253], v212
	ds_read_b64 v[254:255], v213
	v_exp_f32_e32 v83, v83
	v_add_f32_e32 v217, v82, v217
	v_sub_f32_e32 v84, v84, v198
	v_exp_f32_e32 v84, v84
	s_waitcnt lgkmcnt(6)
	v_mfma_f32_32x32x16_bf16 v[64:79], v[232:235], v[114:117], v[64:79]
	ds_read_b64 v[232:233], v212 offset:2048
	ds_read_b64 v[234:235], v213 offset:2048
	v_add_f32_e32 v217, v83, v217
	v_cvt_pk_bf16_f32 v219, v82, v83
	v_sub_f32_e32 v85, v85, v198
	v_exp_f32_e32 v85, v85
	v_add_f32_e32 v217, v84, v217
	s_waitcnt lgkmcnt(7)
	v_mfma_f32_32x32x16_bf16 v[64:79], v[236:239], v[110:113], v[64:79]
	ds_read_b64 v[236:237], v212 offset:4096
	ds_read_b64 v[238:239], v213 offset:4096
	v_sub_f32_e32 v86, v86, v198
	v_exp_f32_e32 v86, v86
	v_add_f32_e32 v217, v85, v217
	v_cvt_pk_bf16_f32 v220, v84, v85
	v_sub_f32_e32 v87, v87, v198
	s_waitcnt lgkmcnt(8)
	v_mfma_f32_32x32x16_bf16 v[64:79], v[240:243], v[106:109], v[64:79]
	ds_read_b64 v[240:241], v212 offset:6144
	ds_read_b64 v[242:243], v213 offset:6144
	v_exp_f32_e32 v87, v87
	v_add_f32_e32 v217, v86, v217
	v_sub_f32_e32 v88, v88, v198
	v_exp_f32_e32 v88, v88
	s_waitcnt lgkmcnt(9)
	v_mfma_f32_32x32x16_bf16 v[64:79], v[244:247], v[102:105], v[64:79]
	ds_read_b64 v[244:245], v214
	ds_read_b64 v[246:247], v215
	v_add_f32_e32 v217, v87, v217
	v_cvt_pk_bf16_f32 v221, v86, v87
	v_sub_f32_e32 v89, v89, v198
	v_exp_f32_e32 v89, v89
	v_add_f32_e32 v217, v88, v217
	s_waitcnt lgkmcnt(10)
	v_mfma_f32_32x32x16_bf16 v[64:79], v[248:251], v[98:101], v[64:79]
	ds_read_b64 v[248:249], v214 offset:2048
	ds_read_b64 v[250:251], v215 offset:2048
	v_sub_f32_e32 v90, v90, v198
	v_exp_f32_e32 v90, v90
	v_add_f32_e32 v217, v89, v217
	v_cvt_pk_bf16_f32 v222, v88, v89
	v_sub_f32_e32 v91, v91, v198
	s_waitcnt lgkmcnt(10)
	v_mfma_f32_32x32x16_bf16 v[48:63], v[252:255], v[218:221], v[48:63]
	ds_read_b64 v[80:81], v214 offset:4096
	ds_read_b64 v[82:83], v215 offset:4096
	ds_read_b64 v[84:85], v214 offset:6144
	ds_read_b64 v[86:87], v215 offset:6144
	v_exp_f32_e32 v91, v91
	v_add_f32_e32 v217, v90, v217
	v_sub_f32_e32 v92, v92, v198
	v_exp_f32_e32 v92, v92
	s_waitcnt lgkmcnt(12)
	v_mfma_f32_32x32x16_bf16 v[32:47], v[232:235], v[218:221], v[32:47]
	v_add_f32_e32 v217, v91, v217
	v_cvt_pk_bf16_f32 v223, v90, v91
	v_sub_f32_e32 v93, v93, v198
	v_exp_f32_e32 v93, v93
	v_add_f32_e32 v217, v92, v217
	s_waitcnt lgkmcnt(10)
	v_mfma_f32_32x32x16_bf16 v[16:31], v[236:239], v[218:221], v[16:31]
	v_sub_f32_e32 v94, v94, v198
	v_exp_f32_e32 v94, v94
	v_add_f32_e32 v217, v93, v217
	v_cvt_pk_bf16_f32 v224, v92, v93
	v_sub_f32_e32 v95, v95, v198
	s_waitcnt lgkmcnt(8)
	v_mfma_f32_32x32x16_bf16 v[0:15], v[240:243], v[218:221], v[0:15]
	v_exp_f32_e32 v95, v95
	v_add_f32_e32 v217, v94, v217
	v_add_f32_e32 v217, v95, v217
	v_cvt_pk_bf16_f32 v225, v94, v95
	v_add_f32_e32 v177, v177, v217
	s_addk_i32 s4, 0x3000
	s_addk_i32 s36, 0x2000
	s_add_i32 s0, s0, 1
	s_add_i32 s1, s1, 1
	s_add_i32 s5, s5, 1
	v_readlane_b32 s6, v227, 16
	v_lshl_add_u64 v[166:167], v[166:167], 0, 64
	v_lshl_add_u64 v[168:169], v[168:169], 0, v[164:165]
	v_lshl_add_u64 v[170:171], v[170:171], 0, v[162:163]
	v_lshl_add_u64 v[172:173], v[172:173], 0, v[96:97]
	s_cmp_eq_u32 s6, s4
	s_waitcnt lgkmcnt(6)
	v_mfma_f32_32x32x16_bf16 v[48:63], v[244:247], v[222:225], v[48:63]
	s_waitcnt lgkmcnt(4)
	v_mfma_f32_32x32x16_bf16 v[32:47], v[248:251], v[222:225], v[32:47]
	s_waitcnt lgkmcnt(2)
	v_mfma_f32_32x32x16_bf16 v[16:31], v[80:83], v[222:225], v[16:31]
	s_waitcnt lgkmcnt(0)
	v_mfma_f32_32x32x16_bf16 v[0:15], v[84:87], v[222:225], v[0:15]
	s_cbranch_scc1 .LBB0_615
	v_mov_b64_e32 v[94:95], v[78:79]
	v_mov_b64_e32 v[92:93], v[76:77]
	v_mov_b64_e32 v[90:91], v[74:75]
	v_mov_b64_e32 v[88:89], v[72:73]
	v_mov_b64_e32 v[86:87], v[70:71]
	v_mov_b64_e32 v[84:85], v[68:69]
	v_mov_b64_e32 v[82:83], v[66:67]
	v_mov_b64_e32 v[80:81], v[64:65]
	s_branch .LBB0_609
